# NSA selected/window tile loops: drop speculative -inf prefill of score regs, skip path fills them (on v059 base, no MLA prio tweak)
# baseline (speedup 1.0000x reference)
.LBB0_1916:
	s_add_i32 s21, s20, -8
	v_mov_b32_e32 v18, s21
	ds_read_b32 v18, v18
	s_waitcnt lgkmcnt(0)
	v_readfirstlane_b32 s2, v18
	s_lshl_b32 s2, s2, 6
	s_cmp_gt_i32 s2, s8
	s_cbranch_scc1 .LBB0_1920
	v_readfirstlane_b32 s2, v18
	s_lshl_b32 s2, s2, 6
	s_or_b32 s2, s2, 63
	s_cmp_le_i32 s2, s16
	s_cbranch_scc1 .LBB0_1920
	v_readfirstlane_b32 s2, v18
	s_ashr_i32 s3, s2, 5
	s_lshl_b32 s3, s3, 2
	s_add_i32 s3, s19, s3
	v_mov_b32_e32 v18, s3
	ds_read_b32 v18, v18
	s_waitcnt lgkmcnt(0)
	v_readfirstlane_b32 s3, v18
	s_lshr_b32 s2, s3, s2
	s_bitcmp0_b32 s2, 0
	s_cbranch_scc1 .LBB0_1920
	v_add_u32_e32 v249, v226, v227
	v_add_u32_e32 v248, v226, v228
	v_add_u32_e32 v26, v226, v229
	v_add_u32_e32 v27, v226, v234
	ds_read_b128 v[130:133], v249 offset:49152
	ds_read_b128 v[134:137], v249 offset:57344
	ds_read_b128 v[138:141], v248 offset:49152
	ds_read_b128 v[186:189], v248 offset:57344
	ds_read_b128 v[200:203], v26 offset:49152
	ds_read_b128 v[230:233], v26 offset:57344
	ds_read_b128 v[238:241], v27 offset:49152
	ds_read_b128 v[18:21], v27 offset:57344
	ds_read_b128 v[242:245], v17
	ds_read_b128 v[22:25], v17 offset:1024
	s_waitcnt lgkmcnt(9)
	v_mfma_f32_32x32x16_bf16 v[96:111], v[130:133], v[180:183], 0
	ds_read_b128 v[130:133], v249 offset:49280
	s_waitcnt lgkmcnt(9)
	v_mfma_f32_32x32x16_bf16 v[112:127], v[134:137], v[180:183], 0
	ds_read_b128 v[134:137], v249 offset:57472
	s_waitcnt lgkmcnt(9)
	v_mfma_f32_32x32x16_bf16 v[96:111], v[138:141], v[176:179], v[96:111]
	ds_read_b128 v[138:141], v248 offset:49280
	s_waitcnt lgkmcnt(9)
	v_mfma_f32_32x32x16_bf16 v[112:127], v[186:189], v[176:179], v[112:127]
	ds_read_b128 v[186:189], v248 offset:57472
	s_waitcnt lgkmcnt(9)
	v_mfma_f32_32x32x16_bf16 v[96:111], v[200:203], v[172:175], v[96:111]
	ds_read_b128 v[200:203], v26 offset:49280
	s_waitcnt lgkmcnt(9)
	v_mfma_f32_32x32x16_bf16 v[112:127], v[230:233], v[172:175], v[112:127]
	ds_read_b128 v[230:233], v26 offset:57472
	s_waitcnt lgkmcnt(9)
	v_mfma_f32_32x32x16_bf16 v[96:111], v[238:241], v[168:171], v[96:111]
	ds_read_b128 v[238:241], v27 offset:49280
	s_waitcnt lgkmcnt(9)
	v_mfma_f32_32x32x16_bf16 v[112:127], v[18:21], v[168:171], v[112:127]
	ds_read_b128 v[18:21], v27 offset:57472
	s_waitcnt lgkmcnt(7)
	v_mfma_f32_32x32x16_bf16 v[96:111], v[130:133], v[164:167], v[96:111]
	s_waitcnt lgkmcnt(6)
	v_mfma_f32_32x32x16_bf16 v[112:127], v[134:137], v[164:167], v[112:127]
	s_waitcnt lgkmcnt(5)
	v_mfma_f32_32x32x16_bf16 v[96:111], v[138:141], v[160:163], v[96:111]
	s_waitcnt lgkmcnt(4)
	v_mfma_f32_32x32x16_bf16 v[112:127], v[186:189], v[160:163], v[112:127]
	s_waitcnt lgkmcnt(3)
	v_mfma_f32_32x32x16_bf16 v[96:111], v[200:203], v[242:245], v[96:111]
	s_waitcnt lgkmcnt(2)
	v_mfma_f32_32x32x16_bf16 v[112:127], v[230:233], v[242:245], v[112:127]
	s_waitcnt lgkmcnt(1)
	v_mfma_f32_32x32x16_bf16 v[96:111], v[238:241], v[22:25], v[96:111]
	s_waitcnt lgkmcnt(0)
	v_mfma_f32_32x32x16_bf16 v[112:127], v[18:21], v[22:25], v[112:127]
	s_branch .LBB0_1921

.LBB0_1937:
	v_cndmask_b32_e64 v14, v14, v184, s[2:3]
	v_sub_f32_e32 v15, v96, v14
	v_sub_f32_e32 v22, v98, v14
	v_sub_f32_e32 v23, v100, v14
	v_sub_f32_e32 v24, v102, v14
	v_sub_f32_e32 v25, v104, v14
	v_sub_f32_e32 v26, v106, v14
	v_sub_f32_e32 v27, v108, v14
	v_sub_f32_e32 v28, v110, v14
	v_exp_f32_e32 v96, v15
	v_exp_f32_e32 v98, v22
	v_exp_f32_e32 v100, v23
	v_exp_f32_e32 v102, v24
	v_exp_f32_e32 v104, v25
	v_exp_f32_e32 v106, v26
	v_exp_f32_e32 v108, v27
	v_exp_f32_e32 v110, v28
	s_waitcnt lgkmcnt(0)
	s_barrier
	v_mov_b32_e32 v15, s22
	ds_read_b32 v15, v15
	s_waitcnt lgkmcnt(0)
	v_readfirstlane_b32 s2, v15
	s_lshl_b32 s2, s2, 6
	s_cmp_gt_i32 s2, s8
	s_cbranch_scc1 .LBB0_1941
	v_readfirstlane_b32 s2, v15
	s_lshl_b32 s2, s2, 6
	s_or_b32 s2, s2, 63
	s_cmp_le_i32 s2, s16
	s_cbranch_scc1 .LBB0_1941
	v_readfirstlane_b32 s2, v15
	s_ashr_i32 s3, s2, 5
	s_lshl_b32 s3, s3, 2
	s_add_i32 s3, s19, s3
	v_mov_b32_e32 v15, s3
	ds_read_b32 v15, v15
	s_waitcnt lgkmcnt(0)
	v_readfirstlane_b32 s3, v15
	s_lshr_b32 s2, s3, s2
	s_bitcmp0_b32 s2, 0
	s_cbranch_scc1 .LBB0_1941
	v_add_u32_e32 v15, v226, v227
	v_add_u32_e32 v249, v226, v228
	v_add_u32_e32 v184, v226, v229
	v_add_u32_e32 v185, v226, v234
	ds_read_b128 v[186:189], v15 offset:32768
	ds_read_b128 v[200:203], v15 offset:40960
	ds_read_b128 v[230:233], v249 offset:32768
	ds_read_b128 v[22:25], v249 offset:40960
	ds_read_b128 v[242:245], v17
	ds_read_b128 v[26:29], v17 offset:1024
	s_waitcnt lgkmcnt(5)
	v_mfma_f32_32x32x16_bf16 v[144:159], v[186:189], v[180:183], 0
	ds_read_b128 v[186:189], v184 offset:32768
	s_waitcnt lgkmcnt(5)
	v_mfma_f32_32x32x16_bf16 v[128:143], v[200:203], v[180:183], 0
	ds_read_b128 v[200:203], v184 offset:40960
	s_waitcnt lgkmcnt(5)
	v_mfma_f32_32x32x16_bf16 v[144:159], v[230:233], v[176:179], v[144:159]
	ds_read_b128 v[230:233], v185 offset:32768
	s_waitcnt lgkmcnt(5)
	v_mfma_f32_32x32x16_bf16 v[128:143], v[22:25], v[176:179], v[128:143]
	ds_read_b128 v[22:25], v185 offset:40960
	s_waitcnt lgkmcnt(3)
	v_mfma_f32_32x32x16_bf16 v[144:159], v[186:189], v[172:175], v[144:159]
	ds_read_b128 v[186:189], v15 offset:32896
	s_waitcnt lgkmcnt(3)
	v_mfma_f32_32x32x16_bf16 v[128:143], v[200:203], v[172:175], v[128:143]
	ds_read_b128 v[200:203], v15 offset:41088
	s_waitcnt lgkmcnt(3)
	v_mfma_f32_32x32x16_bf16 v[144:159], v[230:233], v[168:171], v[144:159]
	ds_read_b128 v[230:233], v249 offset:32896
	s_waitcnt lgkmcnt(3)
	v_mfma_f32_32x32x16_bf16 v[128:143], v[22:25], v[168:171], v[128:143]
	ds_read_b128 v[22:25], v249 offset:41088
	s_waitcnt lgkmcnt(3)
	v_mfma_f32_32x32x16_bf16 v[144:159], v[186:189], v[164:167], v[144:159]
	ds_read_b128 v[186:189], v184 offset:32896
	s_waitcnt lgkmcnt(3)
	v_mfma_f32_32x32x16_bf16 v[128:143], v[200:203], v[164:167], v[128:143]
	ds_read_b128 v[200:203], v184 offset:41088
	s_waitcnt lgkmcnt(3)
	v_mfma_f32_32x32x16_bf16 v[144:159], v[230:233], v[160:163], v[144:159]
	ds_read_b128 v[230:233], v185 offset:32896
	s_waitcnt lgkmcnt(3)
	v_mfma_f32_32x32x16_bf16 v[128:143], v[22:25], v[160:163], v[128:143]
	ds_read_b128 v[22:25], v185 offset:41088
	s_waitcnt lgkmcnt(3)
	v_mfma_f32_32x32x16_bf16 v[144:159], v[186:189], v[242:245], v[144:159]
	s_waitcnt lgkmcnt(2)
	v_mfma_f32_32x32x16_bf16 v[128:143], v[200:203], v[242:245], v[128:143]
	s_waitcnt lgkmcnt(1)
	v_mfma_f32_32x32x16_bf16 v[144:159], v[230:233], v[26:29], v[144:159]
	s_waitcnt lgkmcnt(0)
	v_mfma_f32_32x32x16_bf16 v[128:143], v[22:25], v[26:29], v[128:143]
	s_branch .LBB0_1942
